# prep: the S5 parameter block (one thread per state) runs on workgroups 192-223, which skip the adaLN GEMV, instead of 0-31 (off the phase tail)
# speedup vs baseline: 1.0102x; 1.0102x over previous
.LPREPD_entry:
	s_or_b64 exec, exec, s[10:11]
	v_add_u32_e32 v0, 0xfffe8000, v0
	s_movk_i32 s3, 0x4000
	v_cmp_gt_u32_e32 vcc, s3, v0
	s_and_saveexec_b64 s[10:11], vcc
	s_cbranch_execz .LBB0_408
	s_add_u32 s12, s66, 0x300000
	v_lshlrev_b32_e32 v164, 5, v32
	s_addc_u32 s13, s67, 0
	v_lshl_add_u64 v[2:3], s[66:67], 0, v[164:165]
	s_mov_b64 s[4:5], 0x100000
	v_lshlrev_b32_e32 v164, 2, v32
	s_add_u32 s14, s66, 0x380000
	v_lshl_add_u64 v[2:3], v[2:3], 0, s[4:5]
	v_lshl_add_u64 v[4:5], s[66:67], 0, v[164:165]
	s_mov_b64 s[4:5], 0x200000
	v_ashrrev_i32_e32 v1, 31, v0
	s_addc_u32 s15, s67, 0
	v_lshl_add_u64 v[4:5], v[4:5], 0, s[4:5]
	v_lshlrev_b32_e32 v6, 1, v0
	v_lshlrev_b64 v[8:9], 2, v[0:1]
	v_lshlrev_b64 v[10:11], 6, v[0:1]
	s_mov_b64 s[16:17], 0
	v_lshlrev_b32_e32 v1, 2, v32
	s_branch .LBB0_396
